# v6 stack plus dependency-counter snapshot beside the queue pop (GQA, retention, state units skip satisfied polls)
# speedup vs baseline: 1.0026x; 1.0026x over previous
.LBB0_151:
	v_readlane_b32 s0, v252, 0
	s_mov_b32 s78, s0
	v_readlane_b32 s0, v254, 5
	s_ashr_i32 s2, s0, 2
	s_and_b32 s3, s0, 3
	s_lshl_b32 s0, s2, 6
	s_ashr_i32 s1, s0, 31
	v_writelane_b32 v254, s0, 8
	s_lshl_b32 s79, s2, 5
	s_lshl_b32 s4, s2, 9
	v_writelane_b32 v254, s1, 9
	s_mov_b32 s0, s2
	v_writelane_b32 v254, s0, 10
	s_mov_b64 s[10:11], -1
	s_mov_b64 s[12:13], 0
	v_writelane_b32 v254, s1, 11
	s_lshl_b32 s0, s2, 4
	v_writelane_b32 v254, s0, 12
	v_writelane_b32 v254, s73, 13
	v_writelane_b32 v254, s80, 14
	s_cmp_lt_i32 s3, 2
	s_mov_b64 s[8:9], 0
	v_writelane_b32 v254, s81, 15
	s_cbranch_scc1 .LBB0_359
	s_cmp_eq_u32 s3, 2
	s_mov_b64 s[8:9], -1
	s_cbranch_scc0 .LBB0_358
	v_writelane_b32 v254, s3, 16
	v_cmp_eq_u32_e64 s[42:43], 0, v218
	v_readlane_b32 s0, v254, 8
	v_readlane_b32 s1, v254, 9
	s_lshl_b64 s[2:3], s[0:1], 2
	v_readlane_b32 s0, v252, 13
	s_add_u32 s2, s0, s2
	v_readlane_b32 s0, v252, 14
	s_addc_u32 s3, s0, s3
	v_writelane_b32 v254, s2, 17
	s_nop 1
	v_writelane_b32 v254, s3, 18
	s_nop 0
	v_readlane_b32 s0, v254, 10
	v_readlane_b32 s1, v254, 11
	s_lshl_b32 s0, s0, 3
	s_ashr_i32 s1, s0, 31
	v_writelane_b32 v254, s0, 19
	s_nop 1
	v_writelane_b32 v254, s1, 20
	s_add_u32 s0, s88, 0x4800000
	v_writelane_b32 v254, s0, 21
	s_addc_u32 s0, s89, 0
	v_writelane_b32 v254, s0, 23
	s_add_u32 s0, s88, 0x4e00000
	v_writelane_b32 v254, s0, 24
	s_addc_u32 s0, s89, 0
	v_writelane_b32 v254, s0, 25
	s_add_u32 s0, s88, 0x5000000
	v_writelane_b32 v254, s0, 26
	s_addc_u32 s0, s89, 0
	v_writelane_b32 v254, s0, 27
	s_add_u32 s0, s88, 0x6900000
	v_writelane_b32 v254, s0, 28
	s_addc_u32 s0, s89, 0
	v_writelane_b32 v254, s0, 30
	s_add_u32 s0, s88, 0x8200000
	v_writelane_b32 v254, s0, 31
	s_addc_u32 s0, s89, 0
	v_writelane_b32 v254, s0, 33
	s_add_u32 s0, s88, 0x8e00000
	v_writelane_b32 v254, s0, 34
	s_addc_u32 s0, s89, 0
	v_writelane_b32 v254, s0, 36
	s_add_u32 s0, s88, 0x5800000
	v_writelane_b32 v254, s0, 37
	s_addc_u32 s0, s89, 0
	v_writelane_b32 v254, s0, 39
	s_add_u32 s0, s88, 0xa00000
	v_writelane_b32 v254, s0, 41
	s_addc_u32 s0, s89, 0
	v_writelane_b32 v254, s0, 43
	s_add_u32 s0, s88, 0x400000
	v_writelane_b32 v254, s0, 44
	s_addc_u32 s0, s89, 0
	v_writelane_b32 v254, s0, 46
	s_add_u32 s0, s88, 0x600000
	v_writelane_b32 v254, s0, 48
	s_addc_u32 s0, s89, 0
	v_writelane_b32 v254, s0, 50
	s_add_u32 s0, s88, 0x3c00000
	v_writelane_b32 v254, s0, 52
	s_addc_u32 s0, s89, 0
	v_writelane_b32 v254, s0, 53
	s_add_u32 s0, s88, 0x4000000
	v_writelane_b32 v254, s0, 54
	s_addc_u32 s0, s89, 0
	v_writelane_b32 v254, s0, 56
	s_add_u32 s0, s88, 0x4400000
	v_writelane_b32 v254, s0, 57
	s_addc_u32 s0, s89, 0
	s_cmp_eq_u32 s73, 0
	v_writelane_b32 v254, s0, 58
	s_cselect_b64 s[12:13], -1, 0
	s_add_u32 s0, s88, 0x8000
	v_writelane_b32 v254, s0, 59
	s_addc_u32 s0, s89, 0
	s_add_u32 s14, s88, 0x4200
	v_writelane_b32 v254, s0, 60
	s_addc_u32 s15, s89, 0
	s_and_b32 s0, s73, 3
	s_ashr_i32 s2, s73, 2
	s_lshl_b32 s1, s2, 5
	s_lshl_b32 s2, s2, 12
	s_lshl_b32 s3, s0, 10
	s_or_b32 s80, s2, s3
	s_lshl_b32 s51, s73, 5
	s_lshl_b32 s5, s0, 12
	s_addk_i32 s80, 0x3000
	s_lshl_b32 s16, s73, 10
	s_lshl_b32 s10, s73, 3
	s_and_b32 s6, s51, 32
	s_add_i32 s7, s5, s1
	s_add_i32 s17, s16, 0
	s_add_i32 s38, s80, 0
	s_bfe_u32 s2, s73, 0x10001
	s_cmp_eq_u32 s2, 0
	s_cselect_b64 s[8:9], -1, 0
	v_writelane_b32 v254, s8, 61
	s_add_u32 s5, s88, 0xa200
	s_mov_b32 s81, s1
	v_writelane_b32 v254, s9, 62
	v_writelane_b32 v254, s5, 63
	s_addc_u32 s5, s89, 0
	s_cmp_lt_i32 s73, 4
	v_writelane_b32 v255, s5, 0
	s_cselect_b64 s[8:9], -1, 0
	v_writelane_b32 v255, s8, 2
	s_lshl_b32 s2, s2, 16
	v_readlane_b32 s5, v252, 15
	v_writelane_b32 v255, s9, 3
	s_add_u32 s2, s5, s2
	v_readlane_b32 s5, v252, 16
	s_addc_u32 s5, s5, 0
	v_writelane_b32 v255, s6, 4
	s_lshl_b32 s6, s6, 8
	s_add_u32 s2, s2, s6
	v_writelane_b32 v255, s2, 6
	s_addc_u32 s2, s5, 0
	v_writelane_b32 v255, s2, 7
	s_add_u32 s2, s88, 0x300000
	v_writelane_b32 v255, s2, 8
	s_addc_u32 s2, s89, 0
	s_add_u32 s39, s88, 0x1800
	s_addc_u32 s8, s89, 0
	v_writelane_b32 v255, s2, 9
	s_add_u32 s2, s88, 0x9000
	v_writelane_b32 v255, s2, 10
	s_addc_u32 s2, s89, 0
	v_writelane_b32 v255, s2, 11
	s_lshl_b32 s2, s73, 9
	s_add_i32 s2, s2, 0
	s_add_i32 s2, s2, 0x21800
	v_writelane_b32 v255, s2, 12
	s_add_u32 s18, s88, 0x5900000
	s_mul_i32 s2, s73, 0x2200
	s_addc_u32 s19, s89, 0
	s_add_i32 s9, s2, 0
	s_add_u32 s26, s88, 0x7200000
	s_addc_u32 s27, s89, 0
	s_lshl_b32 s2, s0, 11
	v_writelane_b32 v255, s7, 13
	s_sub_i32 s5, s7, s2
	v_writelane_b32 v255, s5, 14
	s_lshl_b32 s5, s73, 7
	s_add_i32 s6, s5, 0
	s_add_i32 s6, s6, 0x22800
	s_add_u32 s5, s88, 0x9800
	v_writelane_b32 v255, s5, 15
	s_addc_u32 s5, s89, 0
	v_writelane_b32 v255, s5, 16
	s_add_u32 s5, s88, 0x8800
	v_writelane_b32 v255, s5, 17
	s_addc_u32 s5, s89, 0
	v_writelane_b32 v255, s5, 18
	s_lshl_b32 s5, s0, 4
	s_add_i32 s3, s3, 0
	v_writelane_b32 v255, s5, 19
	s_add_i32 s7, s3, 0x2000
	v_writelane_b32 v255, s3, 20
	s_add_u32 s3, s88, 0x4410000
	v_writelane_b32 v255, s3, 22
	s_addc_u32 s3, s89, 0
	v_writelane_b32 v255, s3, 23
	s_add_u32 s3, s88, 0x4010000
	v_writelane_b32 v255, s3, 24
	s_addc_u32 s3, s89, 0
	v_writelane_b32 v255, s3, 25
	s_lshl_b32 s3, s73, 11
	v_writelane_b32 v255, s3, 26
	s_add_i32 s2, s2, s1
	v_writelane_b32 v255, s2, 27
	s_lshl_b32 s2, s0, 9
	s_mulk_i32 s0, 0x3000
	v_writelane_b32 v255, s2, 29
	s_add_i32 s0, s0, s1
	v_writelane_b32 v255, s0, 30
	v_and_b32_e32 v174, 31, v205
	v_add_u32_e32 v174, s79, v174
	v_lshlrev_b32_e32 v174, 4, v174
	v_lshrrev_b32_e32 v175, 5, v205
	v_lshl_add_u32 v174, v175, 12, v174
	v_mov_b32_e32 v175, 0
	v_readlane_b32 s100, v254, 59
	v_readlane_b32 s101, v254, 60
	s_nop 1
	v_lshl_add_u64 v[174:175], s[100:101], 0, v[174:175]
	s_branch .LBB0_156

.LBB0_156:
	s_waitcnt lgkmcnt(0)
	s_barrier
	s_andn2_b64 vcc, exec, s[12:13]
	s_cbranch_vccnz .Lsnap_none
	global_load_dword v178, v[174:175], off sc1
.Lsnap_none:
	s_and_saveexec_b64 s[28:29], s[42:43]
	s_cbranch_execz .LBB0_160
	s_mov_b64 s[40:41], exec
	v_mbcnt_lo_u32_b32 v0, s40, 0
	v_mbcnt_hi_u32_b32 v0, s41, v0
	v_cmp_eq_u32_e32 vcc, 0, v0
	s_and_saveexec_b64 s[34:35], vcc
	s_cbranch_execz .LBB0_159
	s_bcnt1_i32_b64 s0, s[40:41]
	v_mov_b32_e32 v1, s0
	v_readlane_b32 s0, v254, 17
	v_readlane_b32 s1, v254, 18
	s_nop 4
	global_atomic_add v1, v81, v1, s[0:1] sc0

.LBB0_173:
	s_cmpk_lt_i32 s5, 0x60
	s_cselect_b64 s[28:29], -1, 0
	s_cmpk_gt_i32 s5, 0x5f
	s_cselect_b64 s[34:35], -1, 0
	s_add_i32 s11, s5, 0xffffff00
	s_cmpk_lt_u32 s11, 0x60
	s_cselect_b64 s[2:3], -1, 0
	s_or_b64 s[2:3], s[28:29], s[2:3]
	s_andn2_b64 vcc, exec, s[2:3]
	s_cbranch_vccz .LBB0_180
	s_cmpk_lt_u32 s5, 0xc0
	s_cselect_b64 s[44:45], -1, 0
	s_cmpk_gt_u32 s5, 0xbf
	s_cselect_b64 s[46:47], -1, 0
	s_and_b64 vcc, exec, s[46:47]
	s_cbranch_vccz .LBB0_181
	s_add_i32 s0, s5, 0xfffffea0
	s_cmpk_lt_u32 s0, 0x60
	s_cselect_b64 s[48:49], -1, 0
	s_cmpk_gt_u32 s0, 0x5f
	s_mov_b64 s[40:41], 0
	s_cbranch_scc0 .LBB0_265
	s_load_dwordx2 s[2:3], s[86:87], 0x68
	v_readlane_b32 s0, v254, 19
	v_readlane_b32 s1, v254, 20
	s_lshl_b64 s[36:37], s[0:1], 2
	s_waitcnt lgkmcnt(0)
	s_add_u32 s52, s2, s36
	s_addc_u32 s53, s3, s37
	s_cmpk_lt_u32 s5, 0x100
	s_cselect_b64 s[58:59], -1, 0
	s_cmpk_gt_u32 s5, 0xff
	s_cselect_b64 s[56:57], -1, 0
	s_and_b64 vcc, exec, s[56:57]
	s_cbranch_vccz .LBB0_194
	s_and_b32 s0, s5, 0x7fffffc0
	s_cmpk_lg_i32 s0, 0x1c0
	s_cbranch_scc0 .LBB0_195
	s_and_b32 s3, s5, 3
	s_lshl_b32 s0, s3, 2
	v_mov_b32_e32 v0, s0
	global_load_dword v3, v0, s[52:53]
	global_load_dword v2, v0, s[52:53] offset:16
	s_add_i32 s0, s5, 0xfffffe00
	s_and_b32 s2, s0, -4
	v_readlane_b32 s36, v254, 10
	s_andn2_b64 vcc, exec, s[12:13]
	s_add_i32 s2, s2, s36
	v_readlane_b32 s37, v254, 11
	s_cbranch_vccnz .LBB0_199
	v_readlane_b32 s36, v254, 10
	s_mul_i32 s33, s36, 0x7f
	v_readlane_b32 s37, v254, 11
	s_add_i32 s36, s2, s33
	s_ashr_i32 s37, s36, 31
	s_lshl_b64 s[36:37], s[36:37], 2
	v_readlane_b32 s1, v254, 59
	v_mov_b32_e32 v4, v205
	s_add_u32 s36, s1, s36
	v_readlane_b32 s1, v254, 60
	s_addc_u32 s37, s1, s37
	v_lshlrev_b32_e32 v0, 2, v4
	v_ashrrev_i32_e32 v1, 31, v0
	v_lshl_add_u64 v[0:1], v[0:1], 2, s[36:37]
	s_mov_b32 s33, 1
	v_cmp_gt_i32_e64 s[40:41], 1, v4
	v_readlane_b32 s100, v254, 59
	s_lshl_b32 s101, s79, 4
	s_add_i32 s100, s100, s101
	v_subrev_u32_e32 v179, s100, v0
	v_lshrrev_b32_e32 v179, 2, v179
	ds_bpermute_b32 v179, v179, v178
	s_waitcnt lgkmcnt(0)
	v_cmp_gt_u32_e32 vcc, 8, v179
	s_and_b64 vcc, vcc, s[40:41]
	s_cbranch_vccz .LBB0_199
	s_mov_b64 s[62:63], 0
	s_branch .LBB0_184

.LBB0_213:
	s_lshl_b32 s36, s33, 10
	s_addk_i32 s36, 0x1000
	s_lshl_b32 s33, s33, 8
	s_and_b64 s[40:41], s[58:59], exec
	s_cselect_b32 s58, s36, s33
	s_andn2_b64 vcc, exec, s[12:13]
	s_ashr_i32 s59, s58, 31
	s_cbranch_vccnz .LBB0_230
	s_ashr_i32 s33, s58, 8
	s_add_i32 s33, s33, s79
	s_lshl_b32 s40, s33, 2
	s_ashr_i32 s41, s40, 31
	s_lshl_b64 s[40:41], s[40:41], 2
	v_readlane_b32 s1, v254, 59
	v_mov_b32_e32 v4, v205
	s_add_u32 s40, s1, s40
	v_readlane_b32 s1, v254, 60
	s_addc_u32 s41, s1, s41
	v_lshlrev_b32_e32 v0, 2, v4
	v_ashrrev_i32_e32 v1, 31, v0
	v_lshl_add_u64 v[0:1], v[0:1], 2, s[40:41]
	v_cmp_gt_i32_e64 s[40:41], s2, v4
	v_readlane_b32 s100, v254, 59
	s_lshl_b32 s101, s79, 4
	s_add_i32 s100, s100, s101
	v_subrev_u32_e32 v179, s100, v0
	v_lshrrev_b32_e32 v179, 2, v179
	ds_bpermute_b32 v179, v179, v178
	s_waitcnt lgkmcnt(0)
	v_cmp_gt_u32_e32 vcc, 8, v179
	s_and_b64 vcc, vcc, s[40:41]
	s_cbranch_vccz .LBB0_230
	s_mov_b32 s2, 1
	s_mov_b64 s[62:63], 0
	s_branch .LBB0_217

.LBB0_252:
	s_ashr_i32 s0, s40, 8
	s_add_i32 s0, s0, s79
	s_lshl_b32 s52, s0, 2
	s_ashr_i32 s53, s52, 31
	s_and_saveexec_b64 s[56:57], s[42:43]
	s_cbranch_execz .LBB0_264
	s_ashr_i32 s101, s40, 8
	s_add_i32 s101, s101, 32
	s_nop 3
	v_readlane_b32 s100, v178, s101
	s_cmp_gt_u32 s100, 3
	s_cbranch_scc1 .LBB0_264
	s_lshl_b64 s[36:37], s[52:53], 2
	v_readlane_b32 s0, v255, 10
	s_add_u32 s58, s0, s36
	v_readlane_b32 s0, v255, 11
	s_addc_u32 s59, s0, s37
	v_mov_b64_e32 v[32:33], s[58:59]
	global_load_dword v32, v[32:33], off sc1
	s_waitcnt vmcnt(0) lgkmcnt(0)
	v_cmp_gt_u32_e32 vcc, 4, v32
	s_and_b64 exec, exec, vcc
	s_cbranch_execz .LBB0_264
	s_mov_b32 s0, 1
	s_mov_b64 s[62:63], 0
	s_branch .LBB0_256

.LBB0_272:
	s_andn2_b64 vcc, exec, s[12:13]
	s_cbranch_vccnz .LBB0_289
	s_ashr_i32 s33, s46, 8
	s_add_i32 s33, s33, s79
	s_lshl_b32 s40, s33, 2
	s_ashr_i32 s41, s40, 31
	s_lshl_b64 s[40:41], s[40:41], 2
	v_readlane_b32 s1, v254, 59
	v_mov_b32_e32 v2, v205
	s_add_u32 s40, s1, s40
	v_readlane_b32 s1, v254, 60
	s_addc_u32 s41, s1, s41
	v_lshlrev_b32_e32 v0, 2, v2
	v_ashrrev_i32_e32 v1, 31, v0
	v_lshl_add_u64 v[0:1], v[0:1], 2, s[40:41]
	v_cmp_gt_i32_e64 s[40:41], s3, v2
	v_readlane_b32 s100, v254, 59
	s_lshl_b32 s101, s79, 4
	s_add_i32 s100, s100, s101
	v_subrev_u32_e32 v179, s100, v0
	v_lshrrev_b32_e32 v179, 2, v179
	ds_bpermute_b32 v179, v179, v178
	s_waitcnt lgkmcnt(0)
	v_cmp_gt_u32_e32 vcc, 8, v179
	s_and_b64 vcc, vcc, s[40:41]
	s_cbranch_vccz .LBB0_289
	s_mov_b32 s3, 1
	s_mov_b64 s[62:63], 0
	s_branch .LBB0_276

.LBB0_303:
	s_or_b64 exec, exec, s[40:41]
	s_ashr_i32 s0, s3, 8
	s_add_i32 s0, s0, s79
	s_lshl_b32 s40, s0, 2
	s_ashr_i32 s41, s40, 31
	s_and_saveexec_b64 s[44:45], s[42:43]
	s_cbranch_execz .LBB0_315
	s_ashr_i32 s101, s3, 8
	s_add_i32 s101, s101, 32
	s_nop 3
	v_readlane_b32 s100, v178, s101
	s_cmp_gt_u32 s100, 3
	s_cbranch_scc1 .LBB0_315
	s_lshl_b64 s[36:37], s[40:41], 2
	v_readlane_b32 s0, v255, 10
	s_add_u32 s48, s0, s36
	v_readlane_b32 s0, v255, 11
	s_addc_u32 s49, s0, s37
	s_waitcnt lgkmcnt(0)
	v_mov_b64_e32 v[32:33], s[48:49]
	global_load_dword v32, v[32:33], off sc1
	s_waitcnt vmcnt(0) lgkmcnt(0)
	v_cmp_gt_u32_e32 vcc, 4, v32
	s_and_b64 exec, exec, vcc
	s_cbranch_execz .LBB0_315
	s_mov_b32 s0, 1
	s_mov_b64 s[52:53], 0
	s_branch .LBB0_307
